# panel barriers: arrival atomic returns the count and serves as the first poll
# speedup vs baseline: 1.0053x; 1.0053x over previous
; __device__ __forceinline__ unsigned xb_ld(unsigned* p)              { return __hip_atomic_load(p, __ATOMIC_RELAXED, __HIP_MEMORY_SCOPE_AGENT); }
; __device__ __forceinline__ unsigned xb_add(unsigned* p, unsigned v) { return __hip_atomic_fetch_add(p, v, __ATOMIC_RELAXED, __HIP_MEMORY_SCOPE_AGENT); }
; #define XB_SPIN(cond, bar) do { unsigned _sp = 0; while (cond) { __builtin_amdgcn_s_sleep(1); \
;     if ((++_sp & 255u) == 0u) { if (xb_ld(&(bar)[XB_TMO])) break; if (_sp > XB_SPIN_CAP) { atomicAdd(&(bar)[XB_TMO], 1u); break; } } } } while (0)
; __device__ __forceinline__ void xcd_barrier(const XcdBarrier& b) {
;     asm volatile("s_waitcnt vmcnt(0)" ::: "memory");
;     __syncthreads();
;     if (threadIdx.x == 0) {
;         unsigned* bar = b.bar;
;         __builtin_amdgcn_s_waitcnt(0);
;         unsigned nloc = b.st[0], nx = b.st[1];
;         if (nloc == 0u) { xcd_barrier_complete(bar, b.x, nloc, nx); b.st[0] = nloc; b.st[1] = nx; }
;         const unsigned old = xb_add(&bar[XB_XSUB(b.x)], 1u);
;         const unsigned gen = old / nloc;
;         if (old + 1u == (gen + 1u) * nloc) {
;             __builtin_amdgcn_fence(__ATOMIC_RELEASE, "agent");
;             asm volatile("s_waitcnt vmcnt(0)" ::: "memory");
;             const unsigned og = xb_add(&bar[XB_TOP], 1u);
;             const unsigned tg = og / nx;
;             if (og + 1u == (tg + 1u) * nx) xb_add(&bar[XB_TOPGEN], 1u);
;             else XB_SPIN(xb_ld(&bar[XB_TOPGEN]) == tg, bar);
;             __builtin_amdgcn_fence(__ATOMIC_ACQUIRE, "agent");
;             xb_add(&bar[XB_XGEN(b.x)], 1u);
;             asm volatile("s_waitcnt vmcnt(0)" ::: "memory");
;         } else {
;             XB_SPIN(xb_ld(&bar[XB_XGEN(b.x)]) == gen, bar);
;             __builtin_amdgcn_fence(__ATOMIC_ACQUIRE, "agent");
;             asm volatile("s_waitcnt vmcnt(0)" ::: "memory");
;         }
;     }
;     __syncthreads();
; }
.LBB0_252:
	s_cmp_gt_i32 s85, 2
	s_cselect_b64 s[2:3], -1, 0
	s_and_b64 s[4:5], s[6:7], s[2:3]
	s_andn2_b64 vcc, exec, s[4:5]
	s_cbranch_vccnz .LBB0_306
	s_waitcnt vmcnt(0)
	s_barrier
	s_mov_b64 s[4:5], exec
	v_readlane_b32 s6, v251, 18
	v_readlane_b32 s7, v251, 19
	s_and_b64 s[6:7], s[4:5], s[6:7]
	s_mov_b64 exec, s[6:7]
	s_cbranch_execz .LBB0_305
	buffer_inv sc1
	s_and_b32 s10, s88, 7
	s_lshl_b32 s10, s10, 3
	s_bfe_u32 s11, s88, 0x30003
	s_or_b32 s10, s10, s11
	s_lshl_b32 s10, s10, 8
	s_add_u32 s12, s66, 0xfd09000
	s_addc_u32 s13, s67, 0
	v_mov_b32_e32 v1, s10
	v_mov_b32_e32 v2, 1
	global_atomic_add v3, v1, v2, s[12:13] sc0
	s_movk_i32 s11, 4
	s_mov_b32 s14, 0
	v_mov_b32_e32 v5, 0x6000
	global_load_dword v6, v5, s[12:13] sc1
	s_waitcnt vmcnt(0)
	v_add_u32_e32 v3, 1, v3
	v_readfirstlane_b32 s15, v3
	v_readfirstlane_b32 s10, v6
	s_nop 3
	s_cmp_ge_u32 s15, s11
	s_cselect_b32 s15, 1, 0
	s_cmp_ge_u32 s10, 0x80
	s_cselect_b32 s10, 1, 0
	s_and_b32 s15, s15, s10
	s_cmp_lg_u32 s15, 0
	s_cbranch_scc1 .Lls1_ok
.Lls1_spin:
	global_load_dword v3, v1, s[12:13] sc1
	global_load_dword v6, v5, s[12:13] sc1
	s_waitcnt vmcnt(0)
	v_readfirstlane_b32 s15, v3
	v_readfirstlane_b32 s10, v6
	s_nop 3
	s_cmp_ge_u32 s15, s11
	s_cselect_b32 s15, 1, 0
	s_cmp_ge_u32 s10, 0x80
	s_cselect_b32 s10, 1, 0
	s_and_b32 s15, s15, s10
	s_cmp_lg_u32 s15, 0
	s_cbranch_scc1 .Lls1_ok
	s_sleep 1
	s_add_i32 s14, s14, 1
	s_cmp_lt_u32 s14, 0x20000
	s_cbranch_scc1 .Lls1_spin

; __device__ __forceinline__ unsigned xb_ld(unsigned* p)              { return __hip_atomic_load(p, __ATOMIC_RELAXED, __HIP_MEMORY_SCOPE_AGENT); }
; __device__ __forceinline__ unsigned xb_add(unsigned* p, unsigned v) { return __hip_atomic_fetch_add(p, v, __ATOMIC_RELAXED, __HIP_MEMORY_SCOPE_AGENT); }
; #define XB_SPIN(cond, bar) do { unsigned _sp = 0; while (cond) { __builtin_amdgcn_s_sleep(1); \
;     if ((++_sp & 255u) == 0u) { if (xb_ld(&(bar)[XB_TMO])) break; if (_sp > XB_SPIN_CAP) { atomicAdd(&(bar)[XB_TMO], 1u); break; } } } } while (0)
; __device__ __forceinline__ void xcd_barrier(const XcdBarrier& b) {
;     asm volatile("s_waitcnt vmcnt(0)" ::: "memory");
;     __syncthreads();
;     if (threadIdx.x == 0) {
;         unsigned* bar = b.bar;
;         __builtin_amdgcn_s_waitcnt(0);
;         unsigned nloc = b.st[0], nx = b.st[1];
;         if (nloc == 0u) { xcd_barrier_complete(bar, b.x, nloc, nx); b.st[0] = nloc; b.st[1] = nx; }
;         const unsigned old = xb_add(&bar[XB_XSUB(b.x)], 1u);
;         const unsigned gen = old / nloc;
;         if (old + 1u == (gen + 1u) * nloc) {
;             __builtin_amdgcn_fence(__ATOMIC_RELEASE, "agent");
;             asm volatile("s_waitcnt vmcnt(0)" ::: "memory");
;             const unsigned og = xb_add(&bar[XB_TOP], 1u);
;             const unsigned tg = og / nx;
;             if (og + 1u == (tg + 1u) * nx) xb_add(&bar[XB_TOPGEN], 1u);
;             else XB_SPIN(xb_ld(&bar[XB_TOPGEN]) == tg, bar);
;             __builtin_amdgcn_fence(__ATOMIC_ACQUIRE, "agent");
;             xb_add(&bar[XB_XGEN(b.x)], 1u);
;             asm volatile("s_waitcnt vmcnt(0)" ::: "memory");
;         } else {
;             XB_SPIN(xb_ld(&bar[XB_XGEN(b.x)]) == gen, bar);
;             __builtin_amdgcn_fence(__ATOMIC_ACQUIRE, "agent");
;             asm volatile("s_waitcnt vmcnt(0)" ::: "memory");
;         }
;     }
;     __syncthreads();
; }
.LBB0_353:
	s_cmp_gt_i32 s85, 3
	s_cselect_b64 s[2:3], -1, 0
	s_and_b64 s[4:5], s[10:11], s[2:3]
	s_andn2_b64 vcc, exec, s[4:5]
	s_cbranch_vccnz .LBB0_407
	s_waitcnt vmcnt(0)
	s_waitcnt lgkmcnt(0)
	s_barrier
	s_mov_b64 s[4:5], exec
	v_readlane_b32 s6, v251, 18
	v_readlane_b32 s7, v251, 19
	s_and_b64 s[6:7], s[4:5], s[6:7]
	s_mov_b64 exec, s[6:7]
	s_cbranch_execz .LBB0_406
	buffer_inv sc1
	s_and_b32 s10, s88, 7
	s_lshl_b32 s10, s10, 3
	s_bfe_u32 s11, s88, 0x30003
	s_or_b32 s10, s10, s11
	s_lshl_b32 s10, s10, 8
	s_add_u32 s12, s66, 0xfd09000
	s_addc_u32 s13, s67, 0
	v_mov_b32_e32 v1, s10
	v_mov_b32_e32 v2, 1
	global_atomic_add v3, v1, v2, s[12:13] sc0
	v_mov_b32_e32 v5, 0x5800
	global_atomic_add v5, v2, s[12:13]
	s_movk_i32 s11, 8
	s_mov_b32 s14, 0
	s_waitcnt vmcnt(0)
	v_add_u32_e32 v3, 1, v3
	v_readfirstlane_b32 s15, v3
	s_nop 3
	s_cmp_ge_u32 s15, s11
	s_cbranch_scc1 .Lls2_ok

; __device__ __forceinline__ unsigned xb_ld(unsigned* p)              { return __hip_atomic_load(p, __ATOMIC_RELAXED, __HIP_MEMORY_SCOPE_AGENT); }
; __device__ __forceinline__ unsigned xb_add(unsigned* p, unsigned v) { return __hip_atomic_fetch_add(p, v, __ATOMIC_RELAXED, __HIP_MEMORY_SCOPE_AGENT); }
; #define XB_SPIN(cond, bar) do { unsigned _sp = 0; while (cond) { __builtin_amdgcn_s_sleep(1); \
;     if ((++_sp & 255u) == 0u) { if (xb_ld(&(bar)[XB_TMO])) break; if (_sp > XB_SPIN_CAP) { atomicAdd(&(bar)[XB_TMO], 1u); break; } } } } while (0)
; __device__ __forceinline__ void xcd_barrier(const XcdBarrier& b) {
;     asm volatile("s_waitcnt vmcnt(0)" ::: "memory");
;     __syncthreads();
;     if (threadIdx.x == 0) {
;         unsigned* bar = b.bar;
;         __builtin_amdgcn_s_waitcnt(0);
;         unsigned nloc = b.st[0], nx = b.st[1];
;         if (nloc == 0u) { xcd_barrier_complete(bar, b.x, nloc, nx); b.st[0] = nloc; b.st[1] = nx; }
;         const unsigned old = xb_add(&bar[XB_XSUB(b.x)], 1u);
;         const unsigned gen = old / nloc;
;         if (old + 1u == (gen + 1u) * nloc) {
;             __builtin_amdgcn_fence(__ATOMIC_RELEASE, "agent");
;             asm volatile("s_waitcnt vmcnt(0)" ::: "memory");
;             const unsigned og = xb_add(&bar[XB_TOP], 1u);
;             const unsigned tg = og / nx;
;             if (og + 1u == (tg + 1u) * nx) xb_add(&bar[XB_TOPGEN], 1u);
;             else XB_SPIN(xb_ld(&bar[XB_TOPGEN]) == tg, bar);
;             __builtin_amdgcn_fence(__ATOMIC_ACQUIRE, "agent");
;             xb_add(&bar[XB_XGEN(b.x)], 1u);
;             asm volatile("s_waitcnt vmcnt(0)" ::: "memory");
;         } else {
;             XB_SPIN(xb_ld(&bar[XB_XGEN(b.x)]) == gen, bar);
;             __builtin_amdgcn_fence(__ATOMIC_ACQUIRE, "agent");
;             asm volatile("s_waitcnt vmcnt(0)" ::: "memory");
;         }
;     }
;     __syncthreads();
; }
.LBB0_1138:
	s_cmp_gt_i32 s85, 9
	s_cselect_b64 s[0:1], -1, 0
	s_and_b64 s[2:3], s[4:5], s[0:1]
	s_andn2_b64 vcc, exec, s[2:3]
	s_cbranch_vccnz .LBB0_1192
	s_waitcnt vmcnt(0)
	s_waitcnt vmcnt(0) lgkmcnt(0)
	s_barrier
	s_and_saveexec_b64 s[2:3], s[74:75]
	s_cbranch_execz .LBB0_1191
	buffer_inv sc1
	s_and_b32 s4, s88, 7
	s_lshl_b32 s4, s4, 3
	s_bfe_u32 s5, s88, 0x30003
	s_or_b32 s4, s4, s5
	s_lshl_b32 s4, s4, 8
	s_add_u32 s6, s66, 0xfd09000
	s_addc_u32 s7, s67, 0
	v_mov_b32_e32 v1, s4
	v_mov_b32_e32 v2, 1
	global_atomic_add v3, v1, v2, s[6:7] sc0
	v_mov_b32_e32 v5, 0x5000
	global_atomic_add v5, v2, s[6:7]
	s_movk_i32 s5, 12
	s_mov_b32 s8, 0
	s_waitcnt vmcnt(0)
	v_add_u32_e32 v3, 1, v3
	v_readfirstlane_b32 s9, v3
	s_nop 3
	s_cmp_ge_u32 s9, s5
	s_cbranch_scc1 .Lls8_ok

; __device__ __forceinline__ unsigned xb_ld(unsigned* p)              { return __hip_atomic_load(p, __ATOMIC_RELAXED, __HIP_MEMORY_SCOPE_AGENT); }
; __device__ __forceinline__ unsigned xb_add(unsigned* p, unsigned v) { return __hip_atomic_fetch_add(p, v, __ATOMIC_RELAXED, __HIP_MEMORY_SCOPE_AGENT); }
; #define XB_SPIN(cond, bar) do { unsigned _sp = 0; while (cond) { __builtin_amdgcn_s_sleep(1); \
;     if ((++_sp & 255u) == 0u) { if (xb_ld(&(bar)[XB_TMO])) break; if (_sp > XB_SPIN_CAP) { atomicAdd(&(bar)[XB_TMO], 1u); break; } } } } while (0)
; __device__ __forceinline__ void xcd_barrier(const XcdBarrier& b) {
;     asm volatile("s_waitcnt vmcnt(0)" ::: "memory");
;     __syncthreads();
;     if (threadIdx.x == 0) {
;         unsigned* bar = b.bar;
;         __builtin_amdgcn_s_waitcnt(0);
;         unsigned nloc = b.st[0], nx = b.st[1];
;         if (nloc == 0u) { xcd_barrier_complete(bar, b.x, nloc, nx); b.st[0] = nloc; b.st[1] = nx; }
;         const unsigned old = xb_add(&bar[XB_XSUB(b.x)], 1u);
;         const unsigned gen = old / nloc;
;         if (old + 1u == (gen + 1u) * nloc) {
;             __builtin_amdgcn_fence(__ATOMIC_RELEASE, "agent");
;             asm volatile("s_waitcnt vmcnt(0)" ::: "memory");
;             const unsigned og = xb_add(&bar[XB_TOP], 1u);
;             const unsigned tg = og / nx;
;             if (og + 1u == (tg + 1u) * nx) xb_add(&bar[XB_TOPGEN], 1u);
;             else XB_SPIN(xb_ld(&bar[XB_TOPGEN]) == tg, bar);
;             __builtin_amdgcn_fence(__ATOMIC_ACQUIRE, "agent");
;             xb_add(&bar[XB_XGEN(b.x)], 1u);
;             asm volatile("s_waitcnt vmcnt(0)" ::: "memory");
;         } else {
;             XB_SPIN(xb_ld(&bar[XB_XGEN(b.x)]) == gen, bar);
;             __builtin_amdgcn_fence(__ATOMIC_ACQUIRE, "agent");
;             asm volatile("s_waitcnt vmcnt(0)" ::: "memory");
;         }
;     }
;     __syncthreads();
; }
.LBB0_1235:
	s_cmp_gt_i32 s85, 10
	s_cselect_b64 s[2:3], -1, 0
	s_and_b64 s[0:1], s[0:1], s[2:3]
	s_andn2_b64 vcc, exec, s[0:1]
	s_cbranch_vccnz .LBB0_1289
	s_waitcnt vmcnt(0)
	s_waitcnt vmcnt(0) lgkmcnt(0)
	s_barrier
	s_and_saveexec_b64 s[0:1], s[74:75]
	s_cbranch_execz .LBB0_1288
	buffer_inv sc1
	s_and_b32 s4, s88, 7
	s_lshl_b32 s4, s4, 3
	s_bfe_u32 s5, s88, 0x30003
	s_or_b32 s4, s4, s5
	s_lshl_b32 s4, s4, 8
	s_add_u32 s6, s66, 0xfd09000
	s_addc_u32 s7, s67, 0
	v_mov_b32_e32 v1, s4
	v_mov_b32_e32 v2, 1
	global_atomic_add v3, v1, v2, s[6:7] sc0
	s_movk_i32 s5, 16
	s_mov_b32 s8, 0
	v_mov_b32_e32 v5, 0x5000
	global_load_dword v6, v5, s[6:7] sc1
	s_waitcnt vmcnt(0)
	v_add_u32_e32 v3, 1, v3
	v_readfirstlane_b32 s9, v3
	v_readfirstlane_b32 s4, v6
	s_nop 3
	s_cmp_ge_u32 s9, s5
	s_cselect_b32 s9, 1, 0
	s_cmp_ge_u32 s4, s86
	s_cselect_b32 s4, 1, 0
	s_and_b32 s9, s9, s4
	s_cmp_lg_u32 s9, 0
	s_cbranch_scc1 .Lls9_ok
.Lls9_spin:
	global_load_dword v3, v1, s[6:7] sc1
	global_load_dword v6, v5, s[6:7] sc1
	s_waitcnt vmcnt(0)
	v_readfirstlane_b32 s9, v3
	v_readfirstlane_b32 s4, v6
	s_nop 3
	s_cmp_ge_u32 s9, s5
	s_cselect_b32 s9, 1, 0
	s_cmp_ge_u32 s4, s86
	s_cselect_b32 s4, 1, 0
	s_and_b32 s9, s9, s4
	s_cmp_lg_u32 s9, 0
	s_cbranch_scc1 .Lls9_ok
	s_sleep 1
	s_add_i32 s8, s8, 1
	s_cmp_lt_u32 s8, 0x20000
	s_cbranch_scc1 .Lls9_spin

; __device__ __forceinline__ unsigned xb_ld(unsigned* p)              { return __hip_atomic_load(p, __ATOMIC_RELAXED, __HIP_MEMORY_SCOPE_AGENT); }
; __device__ __forceinline__ unsigned xb_add(unsigned* p, unsigned v) { return __hip_atomic_fetch_add(p, v, __ATOMIC_RELAXED, __HIP_MEMORY_SCOPE_AGENT); }
; #define XB_SPIN(cond, bar) do { unsigned _sp = 0; while (cond) { __builtin_amdgcn_s_sleep(1); \
;     if ((++_sp & 255u) == 0u) { if (xb_ld(&(bar)[XB_TMO])) break; if (_sp > XB_SPIN_CAP) { atomicAdd(&(bar)[XB_TMO], 1u); break; } } } } while (0)
; __device__ __forceinline__ void xcd_barrier(const XcdBarrier& b) {
;     asm volatile("s_waitcnt vmcnt(0)" ::: "memory");
;     __syncthreads();
;     if (threadIdx.x == 0) {
;         unsigned* bar = b.bar;
;         __builtin_amdgcn_s_waitcnt(0);
;         unsigned nloc = b.st[0], nx = b.st[1];
;         if (nloc == 0u) { xcd_barrier_complete(bar, b.x, nloc, nx); b.st[0] = nloc; b.st[1] = nx; }
;         const unsigned old = xb_add(&bar[XB_XSUB(b.x)], 1u);
;         const unsigned gen = old / nloc;
;         if (old + 1u == (gen + 1u) * nloc) {
;             __builtin_amdgcn_fence(__ATOMIC_RELEASE, "agent");
;             asm volatile("s_waitcnt vmcnt(0)" ::: "memory");
;             const unsigned og = xb_add(&bar[XB_TOP], 1u);
;             const unsigned tg = og / nx;
;             if (og + 1u == (tg + 1u) * nx) xb_add(&bar[XB_TOPGEN], 1u);
;             else XB_SPIN(xb_ld(&bar[XB_TOPGEN]) == tg, bar);
;             __builtin_amdgcn_fence(__ATOMIC_ACQUIRE, "agent");
;             xb_add(&bar[XB_XGEN(b.x)], 1u);
;             asm volatile("s_waitcnt vmcnt(0)" ::: "memory");
;         } else {
;             XB_SPIN(xb_ld(&bar[XB_XGEN(b.x)]) == gen, bar);
;             __builtin_amdgcn_fence(__ATOMIC_ACQUIRE, "agent");
;             asm volatile("s_waitcnt vmcnt(0)" ::: "memory");
;         }
;     }
;     __syncthreads();
; }
.LBB0_1327:
	s_cmp_gt_i32 s85, 11
	s_cselect_b64 s[2:3], -1, 0
	s_and_b64 s[0:1], s[0:1], s[2:3]
	v_readlane_b32 s48, v252, 22
	s_andn2_b64 vcc, exec, s[0:1]
	v_readlane_b32 s49, v252, 23
	s_cbranch_vccnz .LBB0_1381
	s_waitcnt vmcnt(0)
	s_waitcnt vmcnt(0) lgkmcnt(0)
	s_barrier
	s_and_saveexec_b64 s[0:1], s[74:75]
	s_cbranch_execz .LBB0_1380
	buffer_inv sc1
	s_and_b32 s4, s88, 7
	s_lshl_b32 s4, s4, 3
	s_bfe_u32 s5, s88, 0x30003
	s_or_b32 s4, s4, s5
	s_lshl_b32 s4, s4, 8
	s_add_u32 s6, s66, 0xfd09000
	s_addc_u32 s7, s67, 0
	v_mov_b32_e32 v1, s4
	v_mov_b32_e32 v2, 1
	global_atomic_add v3, v1, v2, s[6:7] sc0
	s_movk_i32 s5, 20
	s_mov_b32 s8, 0
	s_waitcnt vmcnt(0)
	v_add_u32_e32 v3, 1, v3
	v_readfirstlane_b32 s9, v3
	s_nop 3
	s_cmp_ge_u32 s9, s5
	s_cbranch_scc1 .Lls10_ok

; __device__ __forceinline__ unsigned xb_ld(unsigned* p)              { return __hip_atomic_load(p, __ATOMIC_RELAXED, __HIP_MEMORY_SCOPE_AGENT); }
; __device__ __forceinline__ unsigned xb_add(unsigned* p, unsigned v) { return __hip_atomic_fetch_add(p, v, __ATOMIC_RELAXED, __HIP_MEMORY_SCOPE_AGENT); }
; #define XB_SPIN(cond, bar) do { unsigned _sp = 0; while (cond) { __builtin_amdgcn_s_sleep(1); \
;     if ((++_sp & 255u) == 0u) { if (xb_ld(&(bar)[XB_TMO])) break; if (_sp > XB_SPIN_CAP) { atomicAdd(&(bar)[XB_TMO], 1u); break; } } } } while (0)
; __device__ __forceinline__ void xcd_barrier(const XcdBarrier& b) {
;     asm volatile("s_waitcnt vmcnt(0)" ::: "memory");
;     __syncthreads();
;     if (threadIdx.x == 0) {
;         unsigned* bar = b.bar;
;         __builtin_amdgcn_s_waitcnt(0);
;         unsigned nloc = b.st[0], nx = b.st[1];
;         if (nloc == 0u) { xcd_barrier_complete(bar, b.x, nloc, nx); b.st[0] = nloc; b.st[1] = nx; }
;         const unsigned old = xb_add(&bar[XB_XSUB(b.x)], 1u);
;         const unsigned gen = old / nloc;
;         if (old + 1u == (gen + 1u) * nloc) {
;             __builtin_amdgcn_fence(__ATOMIC_RELEASE, "agent");
;             asm volatile("s_waitcnt vmcnt(0)" ::: "memory");
;             const unsigned og = xb_add(&bar[XB_TOP], 1u);
;             const unsigned tg = og / nx;
;             if (og + 1u == (tg + 1u) * nx) xb_add(&bar[XB_TOPGEN], 1u);
;             else XB_SPIN(xb_ld(&bar[XB_TOPGEN]) == tg, bar);
;             __builtin_amdgcn_fence(__ATOMIC_ACQUIRE, "agent");
;             xb_add(&bar[XB_XGEN(b.x)], 1u);
;             asm volatile("s_waitcnt vmcnt(0)" ::: "memory");
;         } else {
;             XB_SPIN(xb_ld(&bar[XB_XGEN(b.x)]) == gen, bar);
;             __builtin_amdgcn_fence(__ATOMIC_ACQUIRE, "agent");
;             asm volatile("s_waitcnt vmcnt(0)" ::: "memory");
;         }
;     }
;     __syncthreads();
; }
.LBB0_1428:
	s_cmp_gt_i32 s85, 12
	s_cselect_b64 s[2:3], -1, 0
	s_and_b64 s[0:1], s[0:1], s[2:3]
	s_andn2_b64 vcc, exec, s[0:1]
	s_cbranch_vccnz .LBB0_1482
	s_waitcnt vmcnt(0)
	s_waitcnt vmcnt(0) lgkmcnt(0)
	s_barrier
	s_and_saveexec_b64 s[0:1], s[74:75]
	s_cbranch_execz .LBB0_1481
	buffer_inv sc1
	s_and_b32 s4, s88, 7
	s_lshl_b32 s4, s4, 3
	s_bfe_u32 s5, s88, 0x30003
	s_or_b32 s4, s4, s5
	s_lshl_b32 s4, s4, 8
	s_add_u32 s6, s66, 0xfd09000
	s_addc_u32 s7, s67, 0
	v_mov_b32_e32 v1, s4
	v_mov_b32_e32 v2, 1
	global_atomic_add v3, v1, v2, s[6:7] sc0
	s_movk_i32 s5, 24
	s_mov_b32 s8, 0
	s_waitcnt vmcnt(0)
	v_add_u32_e32 v3, 1, v3
	v_readfirstlane_b32 s9, v3
	s_nop 3
	s_cmp_ge_u32 s9, s5
	s_cbranch_scc1 .Lls11_ok
